# grid barriers: thread 0 issues its buffer_inv sc1 early (beside the leader's L2 write-back / before a non-leader's first poll) so its latency hides behind the rendezvous
# speedup vs baseline: 1.0068x; 1.0068x over previous
; __device__ __forceinline__ unsigned xb_ld(unsigned* p)              { return __hip_atomic_load(p, __ATOMIC_RELAXED, __HIP_MEMORY_SCOPE_AGENT); }
; __device__ __forceinline__ unsigned xb_add(unsigned* p, unsigned v) { return __hip_atomic_fetch_add(p, v, __ATOMIC_RELAXED, __HIP_MEMORY_SCOPE_AGENT); }
; #define XB_SPIN(cond, bar) do { unsigned _sp = 0; while (cond) { __builtin_amdgcn_s_sleep(1); \
;     if ((++_sp & 255u) == 0u) { if (xb_ld(&(bar)[XB_TMO])) break; if (_sp > XB_SPIN_CAP) { atomicAdd(&(bar)[XB_TMO], 1u); break; } } } } while (0)
; __device__ __forceinline__ void xcd_barrier(const XcdBarrier& b) {
;     ...
;         const unsigned old = xb_add(&bar[XB_XSUB(b.x)], 1u);
;         const unsigned gen = old / nloc;
;         if (old + 1u == (gen + 1u) * nloc) {
;             __builtin_amdgcn_fence(__ATOMIC_RELEASE, "agent");
;             asm volatile("s_waitcnt vmcnt(0)" ::: "memory");
;             const unsigned og = xb_add(&bar[XB_TOP], 1u);
;             const unsigned tg = og / nx;
;             if (og + 1u == (tg + 1u) * nx) xb_add(&bar[XB_TOPGEN], 1u);
;             else XB_SPIN(xb_ld(&bar[XB_TOPGEN]) == tg, bar);
;             __builtin_amdgcn_fence(__ATOMIC_ACQUIRE, "agent");
;             xb_add(&bar[XB_XGEN(b.x)], 1u);
;             asm volatile("s_waitcnt vmcnt(0)" ::: "memory");
;         } else {
;             XB_SPIN(xb_ld(&bar[XB_XGEN(b.x)]) == gen, bar);
;             __builtin_amdgcn_fence(__ATOMIC_ACQUIRE, "agent");
;             asm volatile("s_waitcnt vmcnt(0)" ::: "memory");
.LBB0_51:
	s_or_b64 exec, exec, s[8:9]
	v_cvt_f32_u32_e32 v4, v2
	s_waitcnt vmcnt(0)
	v_readfirstlane_b32 s6, v3
	v_sub_u32_e32 v3, 0, v2
	v_rcp_iflag_f32_e32 v4, v4
	v_add_u32_e32 v5, s6, v1
	v_mul_f32_e32 v4, 0x4f7ffffe, v4
	v_cvt_u32_f32_e32 v4, v4
	v_mul_lo_u32 v1, v3, v4
	v_mul_hi_u32 v1, v4, v1
	v_add_u32_e32 v1, v4, v1
	v_mul_hi_u32 v1, v5, v1
	v_mul_lo_u32 v3, v1, v2
	v_sub_u32_e32 v3, v5, v3
	v_add_u32_e32 v4, 1, v1
	v_cmp_ge_u32_e32 vcc, v3, v2
	s_nop 1
	v_cndmask_b32_e32 v1, v1, v4, vcc
	v_sub_u32_e32 v4, v3, v2
	v_cndmask_b32_e32 v3, v3, v4, vcc
	v_add_u32_e32 v4, 1, v1
	v_cmp_ge_u32_e32 vcc, v3, v2
	v_add_u32_e32 v3, 1, v5
	s_nop 0
	v_cndmask_b32_e32 v1, v1, v4, vcc
	v_mul_lo_u32 v4, v2, v1
	v_add_u32_e32 v2, v4, v2
	v_cmp_ne_u32_e32 vcc, v3, v2
	s_and_saveexec_b64 s[6:7], vcc
	s_xor_b64 s[6:7], exec, s[6:7]
	s_cbranch_execz .LBB0_65
	s_waitcnt lgkmcnt(0)
	buffer_inv sc1
	v_mov_b32_e32 v0, 0x2000
	global_load_dword v0, v0, s[4:5] offset:1024 sc1
	s_add_u32 s10, s4, 0x2400
	s_addc_u32 s11, s5, 0
	s_waitcnt vmcnt(0)
	v_cmp_eq_u32_e32 vcc, v0, v1
	s_and_saveexec_b64 s[8:9], vcc
	s_cbranch_execz .LBB0_64
	s_mov_b32 s22, 1
	s_mov_b64 s[12:13], 0
	v_mov_b32_e32 v0, 0
	s_branch .LBB0_55

; __device__ __forceinline__ unsigned xb_ld(unsigned* p)              { return __hip_atomic_load(p, __ATOMIC_RELAXED, __HIP_MEMORY_SCOPE_AGENT); }
; __device__ __forceinline__ unsigned xb_add(unsigned* p, unsigned v) { return __hip_atomic_fetch_add(p, v, __ATOMIC_RELAXED, __HIP_MEMORY_SCOPE_AGENT); }
; #define XB_SPIN(cond, bar) do { unsigned _sp = 0; while (cond) { __builtin_amdgcn_s_sleep(1); \
;     if ((++_sp & 255u) == 0u) { if (xb_ld(&(bar)[XB_TMO])) break; if (_sp > XB_SPIN_CAP) { atomicAdd(&(bar)[XB_TMO], 1u); break; } } } } while (0)
; __device__ __forceinline__ void xcd_barrier(const XcdBarrier& b) {
;     ...
;         if (old + 1u == (gen + 1u) * nloc) {
;             __builtin_amdgcn_fence(__ATOMIC_RELEASE, "agent");
;             asm volatile("s_waitcnt vmcnt(0)" ::: "memory");
;             const unsigned og = xb_add(&bar[XB_TOP], 1u);
;             const unsigned tg = og / nx;
;             if (og + 1u == (tg + 1u) * nx) xb_add(&bar[XB_TOPGEN], 1u);
;             else XB_SPIN(xb_ld(&bar[XB_TOPGEN]) == tg, bar);
.LBB0_64:
	s_or_b64 exec, exec, s[8:9]
	s_waitcnt vmcnt(0)
	s_waitcnt vmcnt(0)
.LBB0_65:
	s_andn2_saveexec_b64 s[6:7], s[6:7]
	s_cbranch_execz .LBB0_85
	s_mov_b64 s[6:7], exec
	buffer_wbl2 sc1
	buffer_inv sc1
	s_waitcnt lgkmcnt(0)
	s_waitcnt vmcnt(0)
	v_mbcnt_lo_u32_b32 v1, s6, 0
	v_mbcnt_hi_u32_b32 v1, s7, v1
	v_cmp_eq_u32_e32 vcc, 0, v1
	s_and_saveexec_b64 s[8:9], vcc
	s_cbranch_execz .LBB0_68
	s_bcnt1_i32_b64 s6, s[6:7]
	v_mov_b32_e32 v2, 0x3000
	v_mov_b32_e32 v3, s6
	global_atomic_add v2, v2, v3, s[72:73] offset:1024 sc0

; __device__ __forceinline__ unsigned xb_add(unsigned* p, unsigned v) { return __hip_atomic_fetch_add(p, v, __ATOMIC_RELAXED, __HIP_MEMORY_SCOPE_AGENT); }
; __device__ __forceinline__ void xcd_barrier(const XcdBarrier& b) {
;     ...
;             __builtin_amdgcn_fence(__ATOMIC_ACQUIRE, "agent");
;             xb_add(&bar[XB_XGEN(b.x)], 1u);
;             asm volatile("s_waitcnt vmcnt(0)" ::: "memory");
.LBB0_82:
	s_or_b64 exec, exec, s[6:7]
	s_mov_b64 s[6:7], exec
	v_mbcnt_lo_u32_b32 v0, s6, 0
	v_mbcnt_hi_u32_b32 v0, s7, v0
	v_cmp_eq_u32_e32 vcc, 0, v0
	s_waitcnt vmcnt(0)
	s_and_saveexec_b64 s[8:9], vcc
	s_cbranch_execz .LBB0_84
	s_bcnt1_i32_b64 s6, s[6:7]
	v_mov_b32_e32 v0, 0x2000
	v_mov_b32_e32 v1, s6
	global_atomic_add v0, v1, s[4:5] offset:1024
